# v13 + nontemporal loads for the once-read f32 residual in the fused LayerNorm epilogues (64 sites)
# speedup vs baseline: 1.0265x; 1.0033x over previous
.LBB0_46:
	s_lshl_b32 s4, s28, 5
	s_lshl_b32 s5, s6, 8
	s_or_b32 s4, s5, s4
	v_lshrrev_b32_e32 v128, 2, v145
	s_lshl_b32 s14, s27, 8
	v_and_or_b32 v138, v128, 12, s4
	s_add_i32 s4, s14, s24
	v_or_b32_e32 v146, s4, v144
	s_barrier
	s_mov_b32 s4, 0x3fb504f3
	v_lshl_add_u32 v128, v146, 11, v138
	v_lshl_add_u64 v[130:131], v[128:129], 2, s[0:1]
	global_load_dwordx4 v[134:137], v[130:131], off nt
	global_load_dwordx4 v[140:143], v[130:131], off offset:64 nt
	global_load_dwordx4 v[148:151], v[130:131], off offset:512 nt
	global_load_dwordx4 v[152:155], v[130:131], off offset:576 nt
	v_add_u32_e32 v130, 0x8000, v128
	v_mov_b32_e32 v131, v129
	v_lshl_add_u64 v[130:131], v[130:131], 2, s[0:1]
	global_load_dwordx4 v[156:159], v[130:131], off nt
	global_load_dwordx4 v[160:163], v[130:131], off offset:64 nt
	global_load_dwordx4 v[164:167], v[130:131], off offset:512 nt
	global_load_dwordx4 v[168:171], v[130:131], off offset:576 nt
	v_add_u32_e32 v130, 0x10000, v128
	v_mov_b32_e32 v131, v129
	v_lshl_add_u64 v[130:131], v[130:131], 2, s[0:1]
	global_load_dwordx4 v[172:175], v[130:131], off nt
	global_load_dwordx4 v[176:179], v[130:131], off offset:64 nt
	global_load_dwordx4 v[180:183], v[130:131], off offset:512 nt
	global_load_dwordx4 v[184:187], v[130:131], off offset:576 nt
	v_add_u32_e32 v130, 0x18000, v128
	v_mov_b32_e32 v131, v129
	v_lshl_add_u64 v[130:131], v[130:131], 2, s[0:1]
	global_load_dwordx4 v[188:191], v[130:131], off nt
	global_load_dwordx4 v[192:195], v[130:131], off offset:64 nt
	global_load_dwordx4 v[196:199], v[130:131], off offset:512 nt
	global_load_dwordx4 v[200:203], v[130:131], off offset:576 nt
	v_add_u32_e32 v130, 0x40000, v128
	v_mov_b32_e32 v131, v129
	v_lshl_add_u64 v[130:131], v[130:131], 2, s[0:1]
	v_and_b32_e32 v132, 63, v145
	v_cmp_gt_u32_e32 vcc, 16, v132
	s_waitcnt vmcnt(0)
	v_pk_fma_f32 v[94:95], v[136:137], s[4:5], v[94:95] op_sel_hi:[1,0,1]
	v_pk_fma_f32 v[92:93], v[134:135], s[4:5], v[92:93] op_sel_hi:[1,0,1]
	v_pk_fma_f32 v[62:63], v[142:143], s[4:5], v[62:63] op_sel_hi:[1,0,1]
	v_pk_fma_f32 v[60:61], v[140:141], s[4:5], v[60:61] op_sel_hi:[1,0,1]
	v_pk_fma_f32 v[30:31], v[150:151], s[4:5], v[30:31] op_sel_hi:[1,0,1]
	v_pk_fma_f32 v[28:29], v[148:149], s[4:5], v[28:29] op_sel_hi:[1,0,1]
	v_pk_fma_f32 v[14:15], v[154:155], s[4:5], v[14:15] op_sel_hi:[1,0,1]
	v_pk_fma_f32 v[12:13], v[152:153], s[4:5], v[12:13] op_sel_hi:[1,0,1]
	v_pk_fma_f32 v[90:91], v[158:159], s[4:5], v[90:91] op_sel_hi:[1,0,1]
	v_pk_fma_f32 v[88:89], v[156:157], s[4:5], v[88:89] op_sel_hi:[1,0,1]
	v_pk_fma_f32 v[58:59], v[162:163], s[4:5], v[58:59] op_sel_hi:[1,0,1]
	v_pk_fma_f32 v[56:57], v[160:161], s[4:5], v[56:57] op_sel_hi:[1,0,1]
	v_pk_fma_f32 v[26:27], v[166:167], s[4:5], v[26:27] op_sel_hi:[1,0,1]
	v_pk_fma_f32 v[24:25], v[164:165], s[4:5], v[24:25] op_sel_hi:[1,0,1]
	v_pk_fma_f32 v[10:11], v[170:171], s[4:5], v[10:11] op_sel_hi:[1,0,1]
	v_pk_fma_f32 v[8:9], v[168:169], s[4:5], v[8:9] op_sel_hi:[1,0,1]
	v_pk_fma_f32 v[86:87], v[174:175], s[4:5], v[86:87] op_sel_hi:[1,0,1]
	v_pk_fma_f32 v[84:85], v[172:173], s[4:5], v[84:85] op_sel_hi:[1,0,1]
	v_pk_fma_f32 v[54:55], v[178:179], s[4:5], v[54:55] op_sel_hi:[1,0,1]
	v_pk_fma_f32 v[52:53], v[176:177], s[4:5], v[52:53] op_sel_hi:[1,0,1]
	v_pk_fma_f32 v[22:23], v[182:183], s[4:5], v[22:23] op_sel_hi:[1,0,1]
	v_pk_fma_f32 v[20:21], v[180:181], s[4:5], v[20:21] op_sel_hi:[1,0,1]
	v_pk_fma_f32 v[6:7], v[186:187], s[4:5], v[6:7] op_sel_hi:[1,0,1]
	v_pk_fma_f32 v[4:5], v[184:185], s[4:5], v[4:5] op_sel_hi:[1,0,1]
	v_pk_fma_f32 v[82:83], v[190:191], s[4:5], v[82:83] op_sel_hi:[1,0,1]
	v_pk_fma_f32 v[80:81], v[188:189], s[4:5], v[80:81] op_sel_hi:[1,0,1]
	v_pk_fma_f32 v[50:51], v[194:195], s[4:5], v[50:51] op_sel_hi:[1,0,1]
	v_pk_fma_f32 v[48:49], v[192:193], s[4:5], v[48:49] op_sel_hi:[1,0,1]
	v_pk_fma_f32 v[18:19], v[198:199], s[4:5], v[18:19] op_sel_hi:[1,0,1]
	v_pk_fma_f32 v[16:17], v[196:197], s[4:5], v[16:17] op_sel_hi:[1,0,1]
	v_pk_fma_f32 v[2:3], v[202:203], s[4:5], v[2:3] op_sel_hi:[1,0,1]
	v_pk_fma_f32 v[0:1], v[200:201], s[4:5], v[0:1] op_sel_hi:[1,0,1]
	s_nop 0
	global_load_dwordx4 v[134:137], v[130:131], off nt
	global_load_dwordx4 v[140:143], v[130:131], off offset:64 nt
	global_load_dwordx4 v[148:151], v[130:131], off offset:512 nt
	global_load_dwordx4 v[152:155], v[130:131], off offset:576 nt
	v_add_u32_e32 v130, 0x48000, v128
	v_mov_b32_e32 v131, v129
	v_lshl_add_u64 v[130:131], v[130:131], 2, s[0:1]
	global_load_dwordx4 v[156:159], v[130:131], off nt
	global_load_dwordx4 v[160:163], v[130:131], off offset:64 nt
	global_load_dwordx4 v[164:167], v[130:131], off offset:512 nt
	global_load_dwordx4 v[168:171], v[130:131], off offset:576 nt
	v_add_u32_e32 v130, 0x50000, v128
	v_mov_b32_e32 v131, v129
	v_lshl_add_u64 v[130:131], v[130:131], 2, s[0:1]
	v_add_u32_e32 v128, 0x58000, v128
	global_load_dwordx4 v[172:175], v[130:131], off nt
	global_load_dwordx4 v[176:179], v[130:131], off offset:64 nt
	global_load_dwordx4 v[180:183], v[130:131], off offset:512 nt
	global_load_dwordx4 v[184:187], v[130:131], off offset:576 nt
	v_lshl_add_u64 v[130:131], v[128:129], 2, s[0:1]
	global_load_dwordx4 v[188:191], v[130:131], off nt
	global_load_dwordx4 v[192:195], v[130:131], off offset:64 nt
	global_load_dwordx4 v[196:199], v[130:131], off offset:512 nt
	global_load_dwordx4 v[200:203], v[130:131], off offset:576 nt
	v_lshlrev_b32_e32 v128, 2, v132
	v_xor_b32_e32 v130, 64, v128
	v_xor_b32_e32 v128, 0x80, v128
	s_waitcnt vmcnt(15)
	v_pk_fma_f32 v[126:127], v[136:137], s[4:5], v[126:127] op_sel_hi:[1,0,1]
	v_pk_fma_f32 v[124:125], v[134:135], s[4:5], v[124:125] op_sel_hi:[1,0,1]
	v_mov_b32_e32 v134, v93
	v_mov_b32_e32 v135, v94
	v_mov_b32_e32 v136, v92
	v_mov_b32_e32 v137, v95
	s_waitcnt vmcnt(14)
	v_pk_fma_f32 v[108:109], v[140:141], s[4:5], v[108:109] op_sel_hi:[1,0,1]
	v_pk_add_f32 v[134:135], v[134:135], v[136:137]
	v_mov_b32_e32 v136, v61
	v_mov_b32_e32 v137, v62
	v_mov_b32_e32 v140, v60
	v_mov_b32_e32 v141, v63
	v_pk_add_f32 v[136:137], v[136:137], v[140:141]
	v_add_f32_e32 v131, v134, v135
	v_pk_add_f32 v[136:137], v[136:137], v[136:137] op_sel_hi:[0,1]
	v_pk_fma_f32 v[110:111], v[142:143], s[4:5], v[110:111] op_sel_hi:[1,0,1]
	v_add_f32_e32 v135, 0, v131
	v_add_f32_e32 v141, v28, v29
	v_add_f32_e32 v143, v30, v31
	v_mov_b32_e32 v140, v12
	v_mov_b32_e32 v142, v13
	v_mov_b32_e32 v136, v14
	v_mov_b32_e32 v134, v15
	v_pk_add_f32 v[140:141], v[140:141], v[142:143]
	v_pk_add_f32 v[134:135], v[136:137], v[134:135]
	s_waitcnt vmcnt(13)
	v_pk_fma_f32 v[78:79], v[150:151], s[4:5], v[78:79] op_sel_hi:[1,0,1]
	v_pk_add_f32 v[134:135], v[140:141], v[134:135]
	v_pk_fma_f32 v[76:77], v[148:149], s[4:5], v[76:77] op_sel_hi:[1,0,1]
	v_add_f32_e32 v131, v134, v135
	ds_bpermute_b32 v133, v130, v131
	s_waitcnt vmcnt(12)
	v_pk_fma_f32 v[46:47], v[154:155], s[4:5], v[46:47] op_sel_hi:[1,0,1]
	v_pk_fma_f32 v[44:45], v[152:153], s[4:5], v[44:45] op_sel_hi:[1,0,1]
	s_waitcnt vmcnt(11)
	v_pk_fma_f32 v[122:123], v[158:159], s[4:5], v[122:123] op_sel_hi:[1,0,1]
	v_pk_fma_f32 v[120:121], v[156:157], s[4:5], v[120:121] op_sel_hi:[1,0,1]
	s_waitcnt lgkmcnt(0)
	v_add_f32_e32 v131, v131, v133
	ds_bpermute_b32 v133, v128, v131
	s_waitcnt vmcnt(10)
	v_pk_fma_f32 v[106:107], v[162:163], s[4:5], v[106:107] op_sel_hi:[1,0,1]
	v_pk_fma_f32 v[104:105], v[160:161], s[4:5], v[104:105] op_sel_hi:[1,0,1]
	s_waitcnt vmcnt(9)
	v_pk_fma_f32 v[74:75], v[166:167], s[4:5], v[74:75] op_sel_hi:[1,0,1]
	v_pk_fma_f32 v[72:73], v[164:165], s[4:5], v[72:73] op_sel_hi:[1,0,1]
	s_waitcnt lgkmcnt(0)
	v_add_f32_e32 v131, v131, v133
	v_fmamk_f32 v134, v131, 0xbc800000, v95
	v_fmamk_f32 v136, v131, 0xbc800000, v93
	v_fmamk_f32 v133, v131, 0xbc800000, v94
	v_fmamk_f32 v135, v131, 0xbc800000, v92
	v_mul_f32_e32 v136, v136, v136
	v_mul_f32_e32 v134, v134, v134
	v_fmac_f32_e32 v136, v135, v135
	v_fmac_f32_e32 v134, v133, v133
	v_fmamk_f32 v135, v131, 0xbc800000, v63
	v_fmamk_f32 v137, v131, 0xbc800000, v61
	v_add_f32_e32 v133, v136, v134
	v_fmamk_f32 v134, v131, 0xbc800000, v62
	v_fmamk_f32 v136, v131, 0xbc800000, v60
	v_mul_f32_e32 v137, v137, v137
	v_mul_f32_e32 v135, v135, v135
	v_fmac_f32_e32 v137, v136, v136
	v_fmac_f32_e32 v135, v134, v134
	v_add_f32_e32 v134, v137, v135
	v_fmamk_f32 v135, v131, 0xbc800000, v31
	v_fmamk_f32 v137, v131, 0xbc800000, v29
	v_add_f32_e32 v133, v133, v134
	v_fmamk_f32 v134, v131, 0xbc800000, v30
	v_fmamk_f32 v136, v131, 0xbc800000, v28
	v_mul_f32_e32 v137, v137, v137
	v_mul_f32_e32 v135, v135, v135
	v_fmac_f32_e32 v137, v136, v136
	v_fmac_f32_e32 v135, v134, v134
	v_add_f32_e32 v134, v137, v135
	v_fmamk_f32 v135, v131, 0xbc800000, v15
	v_fmamk_f32 v137, v131, 0xbc800000, v13
	v_add_f32_e32 v133, v134, v133
	v_fmamk_f32 v134, v131, 0xbc800000, v14
	v_fmamk_f32 v136, v131, 0xbc800000, v12
	v_mul_f32_e32 v137, v137, v137
	v_mul_f32_e32 v135, v135, v135
	v_fmac_f32_e32 v137, v136, v136
	v_fmac_f32_e32 v135, v134, v134
	v_add_f32_e32 v134, v137, v135
	v_add_f32_e32 v133, v134, v133
	ds_bpermute_b32 v134, v130, v133
	s_waitcnt vmcnt(8)
	v_pk_fma_f32 v[42:43], v[170:171], s[4:5], v[42:43] op_sel_hi:[1,0,1]
	v_pk_fma_f32 v[40:41], v[168:169], s[4:5], v[40:41] op_sel_hi:[1,0,1]
	s_waitcnt vmcnt(7)
	v_pk_fma_f32 v[118:119], v[174:175], s[4:5], v[118:119] op_sel_hi:[1,0,1]
	v_pk_fma_f32 v[116:117], v[172:173], s[4:5], v[116:117] op_sel_hi:[1,0,1]
	s_waitcnt lgkmcnt(0)
	v_add_f32_e32 v133, v133, v134
	ds_bpermute_b32 v134, v128, v133
	s_waitcnt vmcnt(6)
	v_pk_fma_f32 v[102:103], v[178:179], s[4:5], v[102:103] op_sel_hi:[1,0,1]
	v_pk_fma_f32 v[100:101], v[176:177], s[4:5], v[100:101] op_sel_hi:[1,0,1]
	s_waitcnt vmcnt(5)
	v_pk_fma_f32 v[70:71], v[182:183], s[4:5], v[70:71] op_sel_hi:[1,0,1]
	v_pk_fma_f32 v[68:69], v[180:181], s[4:5], v[68:69] op_sel_hi:[1,0,1]
	s_waitcnt vmcnt(4)
	v_pk_fma_f32 v[38:39], v[186:187], s[4:5], v[38:39] op_sel_hi:[1,0,1]
	v_pk_fma_f32 v[36:37], v[184:185], s[4:5], v[36:37] op_sel_hi:[1,0,1]
	s_waitcnt vmcnt(3)
	v_pk_fma_f32 v[114:115], v[190:191], s[4:5], v[114:115] op_sel_hi:[1,0,1]
	v_pk_fma_f32 v[112:113], v[188:189], s[4:5], v[112:113] op_sel_hi:[1,0,1]
	s_waitcnt vmcnt(2)
	v_pk_fma_f32 v[98:99], v[194:195], s[4:5], v[98:99] op_sel_hi:[1,0,1]
	v_pk_fma_f32 v[96:97], v[192:193], s[4:5], v[96:97] op_sel_hi:[1,0,1]
	s_waitcnt vmcnt(1)
	v_pk_fma_f32 v[66:67], v[198:199], s[4:5], v[66:67] op_sel_hi:[1,0,1]
	v_pk_fma_f32 v[64:65], v[196:197], s[4:5], v[64:65] op_sel_hi:[1,0,1]
	s_waitcnt vmcnt(0)
	v_pk_fma_f32 v[34:35], v[202:203], s[4:5], v[34:35] op_sel_hi:[1,0,1]
	v_pk_fma_f32 v[32:33], v[200:201], s[4:5], v[32:33] op_sel_hi:[1,0,1]
	s_lshl_b32 s4, s28, 3
	s_add_i32 s8, s4, 0
	s_and_saveexec_b64 s[4:5], vcc
	v_readlane_b32 s30, v255, 3
	v_readlane_b32 s31, v255, 4
	s_cbranch_execz .LBB0_48
	s_lshl_b32 s9, s26, 11
	s_add_i32 s9, s8, s9
	v_mul_f32_e32 v136, 0x3c800000, v131
	v_lshl_add_u32 v131, v144, 5, s9
	s_waitcnt lgkmcnt(0)
	v_add_f32_e32 v137, v133, v134
	ds_write_b64 v131, v[136:137]

.LBB0_127:
	v_readlane_b32 s4, v253, 9
	s_add_i32 s4, s4, 3
	v_readlane_b32 s36, v254, 51
	v_readlane_b32 s5, v253, 10
	s_cmp_lt_u32 s4, 9
	v_readlane_b32 s37, v254, 52
	s_cselect_b32 s5, s37, s1
	s_cselect_b32 s4, s36, s0
	s_lshl_b32 s8, s28, 5
	s_lshl_b32 s9, s6, 8
	s_or_b32 s8, s9, s8
	v_lshrrev_b32_e32 v128, 2, v145
	v_and_or_b32 v138, v128, 12, s8
	s_lshl_b32 s8, s27, 8
	s_add_i32 s9, s8, s24
	v_or_b32_e32 v146, s9, v144
	s_barrier
	s_mov_b32 s10, 0x3fb504f3
	v_lshl_add_u32 v128, v146, 11, v138
	v_lshl_add_u64 v[130:131], v[128:129], 2, s[4:5]
	global_load_dwordx4 v[134:137], v[130:131], off nt
	global_load_dwordx4 v[140:143], v[130:131], off offset:64 nt
	global_load_dwordx4 v[148:151], v[130:131], off offset:512 nt
	global_load_dwordx4 v[152:155], v[130:131], off offset:576 nt
	v_add_u32_e32 v130, 0x8000, v128
	v_mov_b32_e32 v131, v129
	v_lshl_add_u64 v[130:131], v[130:131], 2, s[4:5]
	global_load_dwordx4 v[156:159], v[130:131], off nt
	global_load_dwordx4 v[160:163], v[130:131], off offset:64 nt
	global_load_dwordx4 v[164:167], v[130:131], off offset:512 nt
	global_load_dwordx4 v[168:171], v[130:131], off offset:576 nt
	v_add_u32_e32 v130, 0x10000, v128
	v_mov_b32_e32 v131, v129
	v_lshl_add_u64 v[130:131], v[130:131], 2, s[4:5]
	global_load_dwordx4 v[172:175], v[130:131], off nt
	global_load_dwordx4 v[176:179], v[130:131], off offset:64 nt
	global_load_dwordx4 v[180:183], v[130:131], off offset:512 nt
	global_load_dwordx4 v[184:187], v[130:131], off offset:576 nt
	v_add_u32_e32 v130, 0x18000, v128
	v_mov_b32_e32 v131, v129
	v_lshl_add_u64 v[130:131], v[130:131], 2, s[4:5]
	global_load_dwordx4 v[188:191], v[130:131], off nt
	global_load_dwordx4 v[192:195], v[130:131], off offset:64 nt
	global_load_dwordx4 v[196:199], v[130:131], off offset:512 nt
	global_load_dwordx4 v[200:203], v[130:131], off offset:576 nt
	v_add_u32_e32 v130, 0x40000, v128
	v_mov_b32_e32 v131, v129
	v_lshl_add_u64 v[130:131], v[130:131], 2, s[4:5]
	v_and_b32_e32 v132, 63, v145
	v_cmp_gt_u32_e32 vcc, 16, v132
	v_readlane_b32 s38, v254, 53
	v_readlane_b32 s39, v254, 54
	v_readlane_b32 s40, v254, 55
	v_readlane_b32 s41, v254, 56
	v_readlane_b32 s42, v254, 57
	v_readlane_b32 s43, v254, 58
	v_readlane_b32 s44, v254, 59
	v_readlane_b32 s45, v254, 60
	v_readlane_b32 s46, v254, 61
	v_readlane_b32 s47, v254, 62
	v_readlane_b32 s48, v254, 63
	v_readlane_b32 s49, v255, 0
	v_readlane_b32 s50, v255, 1
	v_readlane_b32 s51, v255, 2
	s_waitcnt vmcnt(0)
	v_pk_fma_f32 v[94:95], v[136:137], s[10:11], v[94:95] op_sel_hi:[1,0,1]
	v_pk_fma_f32 v[92:93], v[134:135], s[10:11], v[92:93] op_sel_hi:[1,0,1]
	v_pk_fma_f32 v[62:63], v[142:143], s[10:11], v[62:63] op_sel_hi:[1,0,1]
	v_pk_fma_f32 v[60:61], v[140:141], s[10:11], v[60:61] op_sel_hi:[1,0,1]
	v_pk_fma_f32 v[30:31], v[150:151], s[10:11], v[30:31] op_sel_hi:[1,0,1]
	v_pk_fma_f32 v[28:29], v[148:149], s[10:11], v[28:29] op_sel_hi:[1,0,1]
	v_pk_fma_f32 v[14:15], v[154:155], s[10:11], v[14:15] op_sel_hi:[1,0,1]
	v_pk_fma_f32 v[12:13], v[152:153], s[10:11], v[12:13] op_sel_hi:[1,0,1]
	v_pk_fma_f32 v[90:91], v[158:159], s[10:11], v[90:91] op_sel_hi:[1,0,1]
	v_pk_fma_f32 v[88:89], v[156:157], s[10:11], v[88:89] op_sel_hi:[1,0,1]
	v_pk_fma_f32 v[58:59], v[162:163], s[10:11], v[58:59] op_sel_hi:[1,0,1]
	v_pk_fma_f32 v[56:57], v[160:161], s[10:11], v[56:57] op_sel_hi:[1,0,1]
	v_pk_fma_f32 v[26:27], v[166:167], s[10:11], v[26:27] op_sel_hi:[1,0,1]
	v_pk_fma_f32 v[24:25], v[164:165], s[10:11], v[24:25] op_sel_hi:[1,0,1]
	v_pk_fma_f32 v[10:11], v[170:171], s[10:11], v[10:11] op_sel_hi:[1,0,1]
	v_pk_fma_f32 v[8:9], v[168:169], s[10:11], v[8:9] op_sel_hi:[1,0,1]
	v_pk_fma_f32 v[86:87], v[174:175], s[10:11], v[86:87] op_sel_hi:[1,0,1]
	v_pk_fma_f32 v[84:85], v[172:173], s[10:11], v[84:85] op_sel_hi:[1,0,1]
	v_pk_fma_f32 v[54:55], v[178:179], s[10:11], v[54:55] op_sel_hi:[1,0,1]
	v_pk_fma_f32 v[52:53], v[176:177], s[10:11], v[52:53] op_sel_hi:[1,0,1]
	v_pk_fma_f32 v[22:23], v[182:183], s[10:11], v[22:23] op_sel_hi:[1,0,1]
	v_pk_fma_f32 v[20:21], v[180:181], s[10:11], v[20:21] op_sel_hi:[1,0,1]
	v_pk_fma_f32 v[6:7], v[186:187], s[10:11], v[6:7] op_sel_hi:[1,0,1]
	v_pk_fma_f32 v[4:5], v[184:185], s[10:11], v[4:5] op_sel_hi:[1,0,1]
	v_pk_fma_f32 v[82:83], v[190:191], s[10:11], v[82:83] op_sel_hi:[1,0,1]
	v_pk_fma_f32 v[80:81], v[188:189], s[10:11], v[80:81] op_sel_hi:[1,0,1]
	v_pk_fma_f32 v[50:51], v[194:195], s[10:11], v[50:51] op_sel_hi:[1,0,1]
	v_pk_fma_f32 v[48:49], v[192:193], s[10:11], v[48:49] op_sel_hi:[1,0,1]
	v_pk_fma_f32 v[18:19], v[198:199], s[10:11], v[18:19] op_sel_hi:[1,0,1]
	v_pk_fma_f32 v[16:17], v[196:197], s[10:11], v[16:17] op_sel_hi:[1,0,1]
	v_pk_fma_f32 v[2:3], v[202:203], s[10:11], v[2:3] op_sel_hi:[1,0,1]
	v_pk_fma_f32 v[0:1], v[200:201], s[10:11], v[0:1] op_sel_hi:[1,0,1]
	s_nop 0
	global_load_dwordx4 v[134:137], v[130:131], off nt
	global_load_dwordx4 v[140:143], v[130:131], off offset:64 nt
	global_load_dwordx4 v[148:151], v[130:131], off offset:512 nt
	global_load_dwordx4 v[152:155], v[130:131], off offset:576 nt
	v_add_u32_e32 v130, 0x48000, v128
	v_mov_b32_e32 v131, v129
	v_lshl_add_u64 v[130:131], v[130:131], 2, s[4:5]
	global_load_dwordx4 v[156:159], v[130:131], off nt
	global_load_dwordx4 v[160:163], v[130:131], off offset:64 nt
	global_load_dwordx4 v[164:167], v[130:131], off offset:512 nt
	global_load_dwordx4 v[168:171], v[130:131], off offset:576 nt
	v_add_u32_e32 v130, 0x50000, v128
	v_mov_b32_e32 v131, v129
	v_lshl_add_u64 v[130:131], v[130:131], 2, s[4:5]
	v_add_u32_e32 v128, 0x58000, v128
	global_load_dwordx4 v[172:175], v[130:131], off nt
	global_load_dwordx4 v[176:179], v[130:131], off offset:64 nt
	global_load_dwordx4 v[180:183], v[130:131], off offset:512 nt
	global_load_dwordx4 v[184:187], v[130:131], off offset:576 nt
	v_lshl_add_u64 v[130:131], v[128:129], 2, s[4:5]
	global_load_dwordx4 v[188:191], v[130:131], off nt
	global_load_dwordx4 v[192:195], v[130:131], off offset:64 nt
	global_load_dwordx4 v[196:199], v[130:131], off offset:512 nt
	global_load_dwordx4 v[200:203], v[130:131], off offset:576 nt
	v_lshlrev_b32_e32 v128, 2, v132
	v_xor_b32_e32 v130, 64, v128
	v_xor_b32_e32 v128, 0x80, v128
	s_lshl_b32 s4, s28, 3
	s_add_i32 s9, s4, 0
	s_waitcnt vmcnt(15)
	v_pk_fma_f32 v[126:127], v[136:137], s[10:11], v[126:127] op_sel_hi:[1,0,1]
	v_pk_fma_f32 v[124:125], v[134:135], s[10:11], v[124:125] op_sel_hi:[1,0,1]
	v_mov_b32_e32 v134, v93
	v_mov_b32_e32 v135, v94
	v_mov_b32_e32 v136, v92
	v_mov_b32_e32 v137, v95
	s_waitcnt vmcnt(14)
	v_pk_fma_f32 v[108:109], v[140:141], s[10:11], v[108:109] op_sel_hi:[1,0,1]
	v_pk_add_f32 v[134:135], v[134:135], v[136:137]
	v_mov_b32_e32 v136, v61
	v_mov_b32_e32 v137, v62
	v_mov_b32_e32 v140, v60
	v_mov_b32_e32 v141, v63
	v_pk_add_f32 v[136:137], v[136:137], v[140:141]
	v_add_f32_e32 v131, v134, v135
	v_pk_add_f32 v[136:137], v[136:137], v[136:137] op_sel_hi:[0,1]
	v_pk_fma_f32 v[110:111], v[142:143], s[10:11], v[110:111] op_sel_hi:[1,0,1]
	v_add_f32_e32 v135, 0, v131
	v_add_f32_e32 v141, v28, v29
	v_add_f32_e32 v143, v30, v31
	v_mov_b32_e32 v140, v12
	v_mov_b32_e32 v142, v13
	v_mov_b32_e32 v136, v14
	v_mov_b32_e32 v134, v15
	v_pk_add_f32 v[140:141], v[140:141], v[142:143]
	v_pk_add_f32 v[134:135], v[136:137], v[134:135]
	s_waitcnt vmcnt(13)
	v_pk_fma_f32 v[78:79], v[150:151], s[10:11], v[78:79] op_sel_hi:[1,0,1]
	v_pk_add_f32 v[134:135], v[140:141], v[134:135]
	v_pk_fma_f32 v[76:77], v[148:149], s[10:11], v[76:77] op_sel_hi:[1,0,1]
	v_add_f32_e32 v131, v134, v135
	ds_bpermute_b32 v133, v130, v131
	s_waitcnt vmcnt(12)
	v_pk_fma_f32 v[46:47], v[154:155], s[10:11], v[46:47] op_sel_hi:[1,0,1]
	v_pk_fma_f32 v[44:45], v[152:153], s[10:11], v[44:45] op_sel_hi:[1,0,1]
	s_waitcnt vmcnt(11)
	v_pk_fma_f32 v[122:123], v[158:159], s[10:11], v[122:123] op_sel_hi:[1,0,1]
	v_pk_fma_f32 v[120:121], v[156:157], s[10:11], v[120:121] op_sel_hi:[1,0,1]
	s_waitcnt lgkmcnt(0)
	v_add_f32_e32 v131, v131, v133
	ds_bpermute_b32 v133, v128, v131
	s_waitcnt vmcnt(10)
	v_pk_fma_f32 v[106:107], v[162:163], s[10:11], v[106:107] op_sel_hi:[1,0,1]
	v_pk_fma_f32 v[104:105], v[160:161], s[10:11], v[104:105] op_sel_hi:[1,0,1]
	s_waitcnt vmcnt(9)
	v_pk_fma_f32 v[74:75], v[166:167], s[10:11], v[74:75] op_sel_hi:[1,0,1]
	v_pk_fma_f32 v[72:73], v[164:165], s[10:11], v[72:73] op_sel_hi:[1,0,1]
	s_waitcnt lgkmcnt(0)
	v_add_f32_e32 v131, v131, v133
	v_fmamk_f32 v134, v131, 0xbc800000, v95
	v_fmamk_f32 v136, v131, 0xbc800000, v93
	v_fmamk_f32 v133, v131, 0xbc800000, v94
	v_fmamk_f32 v135, v131, 0xbc800000, v92
	v_mul_f32_e32 v136, v136, v136
	v_mul_f32_e32 v134, v134, v134
	v_fmac_f32_e32 v136, v135, v135
	v_fmac_f32_e32 v134, v133, v133
	v_fmamk_f32 v135, v131, 0xbc800000, v63
	v_fmamk_f32 v137, v131, 0xbc800000, v61
	v_add_f32_e32 v133, v136, v134
	v_fmamk_f32 v134, v131, 0xbc800000, v62
	v_fmamk_f32 v136, v131, 0xbc800000, v60
	v_mul_f32_e32 v137, v137, v137
	v_mul_f32_e32 v135, v135, v135
	v_fmac_f32_e32 v137, v136, v136
	v_fmac_f32_e32 v135, v134, v134
	v_add_f32_e32 v134, v137, v135
	v_fmamk_f32 v135, v131, 0xbc800000, v31
	v_fmamk_f32 v137, v131, 0xbc800000, v29
	v_add_f32_e32 v133, v133, v134
	v_fmamk_f32 v134, v131, 0xbc800000, v30
	v_fmamk_f32 v136, v131, 0xbc800000, v28
	v_mul_f32_e32 v137, v137, v137
	v_mul_f32_e32 v135, v135, v135
	v_fmac_f32_e32 v137, v136, v136
	v_fmac_f32_e32 v135, v134, v134
	v_add_f32_e32 v134, v137, v135
	v_fmamk_f32 v135, v131, 0xbc800000, v15
	v_fmamk_f32 v137, v131, 0xbc800000, v13
	v_add_f32_e32 v133, v134, v133
	v_fmamk_f32 v134, v131, 0xbc800000, v14
	v_fmamk_f32 v136, v131, 0xbc800000, v12
	v_mul_f32_e32 v137, v137, v137
	v_mul_f32_e32 v135, v135, v135
	v_fmac_f32_e32 v137, v136, v136
	v_fmac_f32_e32 v135, v134, v134
	v_add_f32_e32 v134, v137, v135
	v_add_f32_e32 v133, v134, v133
	ds_bpermute_b32 v134, v130, v133
	s_waitcnt vmcnt(8)
	v_pk_fma_f32 v[42:43], v[170:171], s[10:11], v[42:43] op_sel_hi:[1,0,1]
	v_pk_fma_f32 v[40:41], v[168:169], s[10:11], v[40:41] op_sel_hi:[1,0,1]
	s_waitcnt vmcnt(7)
	v_pk_fma_f32 v[118:119], v[174:175], s[10:11], v[118:119] op_sel_hi:[1,0,1]
	v_pk_fma_f32 v[116:117], v[172:173], s[10:11], v[116:117] op_sel_hi:[1,0,1]
	s_waitcnt lgkmcnt(0)
	v_add_f32_e32 v133, v133, v134
	ds_bpermute_b32 v134, v128, v133
	s_waitcnt vmcnt(6)
	v_pk_fma_f32 v[102:103], v[178:179], s[10:11], v[102:103] op_sel_hi:[1,0,1]
	v_pk_fma_f32 v[100:101], v[176:177], s[10:11], v[100:101] op_sel_hi:[1,0,1]
	s_waitcnt vmcnt(5)
	v_pk_fma_f32 v[70:71], v[182:183], s[10:11], v[70:71] op_sel_hi:[1,0,1]
	v_pk_fma_f32 v[68:69], v[180:181], s[10:11], v[68:69] op_sel_hi:[1,0,1]
	s_waitcnt vmcnt(4)
	v_pk_fma_f32 v[38:39], v[186:187], s[10:11], v[38:39] op_sel_hi:[1,0,1]
	v_pk_fma_f32 v[36:37], v[184:185], s[10:11], v[36:37] op_sel_hi:[1,0,1]
	s_waitcnt vmcnt(3)
	v_pk_fma_f32 v[114:115], v[190:191], s[10:11], v[114:115] op_sel_hi:[1,0,1]
	v_pk_fma_f32 v[112:113], v[188:189], s[10:11], v[112:113] op_sel_hi:[1,0,1]
	s_waitcnt vmcnt(2)
	v_pk_fma_f32 v[98:99], v[194:195], s[10:11], v[98:99] op_sel_hi:[1,0,1]
	v_pk_fma_f32 v[96:97], v[192:193], s[10:11], v[96:97] op_sel_hi:[1,0,1]
	s_waitcnt vmcnt(1)
	v_pk_fma_f32 v[66:67], v[198:199], s[10:11], v[66:67] op_sel_hi:[1,0,1]
	v_pk_fma_f32 v[64:65], v[196:197], s[10:11], v[64:65] op_sel_hi:[1,0,1]
	s_waitcnt vmcnt(0)
	v_pk_fma_f32 v[34:35], v[202:203], s[10:11], v[34:35] op_sel_hi:[1,0,1]
	v_pk_fma_f32 v[32:33], v[200:201], s[10:11], v[32:33] op_sel_hi:[1,0,1]
	s_nop 0
	s_and_saveexec_b64 s[4:5], vcc
	v_readlane_b32 s30, v255, 3
	v_readlane_b32 s31, v255, 4
	s_cbranch_execz .LBB0_129
	s_lshl_b32 s10, s26, 11
	s_add_i32 s10, s9, s10
	v_mul_f32_e32 v136, 0x3c800000, v131
	v_lshl_add_u32 v131, v144, 5, s10
	s_waitcnt lgkmcnt(0)
	v_add_f32_e32 v137, v133, v134
	ds_write_b64 v131, v[136:137]
